# SB: stream-0 score MFMAs write v[18:33] directly; v_mov_b64 copies and inactive-stream zero fill removed
# baseline (speedup 1.0000x reference)
; #define LAS __attribute__((address_space(3)))
; DI f32x16 zero16() { f32x16 z; for (int i = 0; i < 16; ++i) z[i] = 0.f; return z; }
; #define MFMA32(a, b, c) __builtin_amdgcn_mfma_f32_32x32x16_bf16((a), (b), (c), 0, 0, 0)
; DI void sb_block2(const Params& p, LAS unsigned char* lds, int bh, int qb2, int tid) {
;     ...
;                 const LAS unsigned char* kp = base + (sub * 32 + r) * SB_ROW + h * 16;
;                 const bool act0 = !done[0] && kb <= q0[0], act1 = !done[1] && kb <= q0[1];
;                 if (act0 || act1) {
;                     bf16x8 kf[4], vf[4];
; #pragma unroll
;                     for (int ks = 0; ks < 4; ++ks) kf[ks] = *(const LAS bf16x8*)(kp + ks * 32);
; #pragma unroll
;                     for (int dt = 0; dt < 2; ++dt)
; #pragma unroll
;                         for (int s2 = 0; s2 < 2; ++s2) vf[dt * 2 + s2] = *(const LAS bf16x8*)(base + SB_KBYTES + (dt * 32 + r) * SB_ROW + (sub * 32 + 16 * h + 8 * s2) * 2);
;                     f32x16 zz[2];
; #pragma unroll
;                     for (int g = 0; g < 2; ++g) {
;                         zz[g] = zero16();
;                         if (g == 0 ? act0 : act1) {
; #pragma unroll
;                             for (int ks = 0; ks < 4; ++ks) zz[g] = MFMA32(kf[ks], qf[g][ks], zz[g]);
;                         }
;                     }
.LBB0_841:
	s_lshr_b32 s74, s69, 3
	s_cmp_le_i32 s59, s56
	s_cselect_b64 s[0:1], -1, 0
	s_xor_b64 s[2:3], s[62:63], -1
	s_and_b64 s[48:49], s[0:1], s[2:3]
	s_bitcmp1_b32 s81, 0
	s_cselect_b64 s[0:1], -1, 0
	s_cmp_le_i32 s59, s58
	s_cselect_b64 s[2:3], -1, 0
	s_xor_b64 s[0:1], s[0:1], -1
	s_and_b64 s[2:3], s[2:3], s[0:1]
	s_or_b64 s[0:1], s[48:49], s[2:3]
	s_andn2_b64 vcc, exec, s[0:1]
	s_cbranch_vccnz .LBB0_849
	ds_read_b128 v[174:177], v147
	ds_read_b128 v[170:173], v147 offset:32
	ds_read_b128 v[166:169], v147 offset:64
	ds_read_b128 v[162:165], v147 offset:96
	ds_read_b128 v[158:161], v146 offset:9216
	ds_read_b128 v[150:153], v146 offset:9232
	ds_read_b128 v[154:157], v146 offset:13824
	ds_read_b128 v[146:149], v146 offset:13840
	v_cndmask_b32_e64 v0, 0, 1, s[48:49]
	v_cmp_ne_u32_e64 s[0:1], 1, v0
	s_andn2_b64 vcc, exec, s[48:49]
	s_cbranch_vccnz .LBB0_844
	s_waitcnt lgkmcnt(0)
	v_mfma_f32_32x32x16_bf16 v[18:33], v[174:177], v[114:117], 0
	v_mfma_f32_32x32x16_bf16 v[18:33], v[170:173], v[118:121], v[18:33]
	v_mfma_f32_32x32x16_bf16 v[18:33], v[166:169], v[122:125], v[18:33]
	v_mfma_f32_32x32x16_bf16 v[18:33], v[162:165], v[126:129], v[18:33]
	s_branch .LBB0_845
.LBB0_844:
.LBB0_845:
	v_cndmask_b32_e64 v0, 0, 1, s[2:3]
	v_cmp_ne_u32_e64 s[48:49], 1, v0
	s_andn2_b64 vcc, exec, s[2:3]
	s_nop 7
	s_cbranch_vccnz .LBB0_934
	s_waitcnt lgkmcnt(0)
	v_mfma_f32_32x32x16_bf16 v[34:49], v[174:177], v[130:133], 0
	v_mfma_f32_32x32x16_bf16 v[34:49], v[170:173], v[134:137], v[34:49]
	v_mfma_f32_32x32x16_bf16 v[34:49], v[166:169], v[138:141], v[34:49]
	v_mfma_f32_32x32x16_bf16 v[34:49], v[162:165], v[142:145], v[34:49]
	s_and_b64 vcc, exec, s[0:1]
	s_cbranch_vccz .LBB0_935

; #define LAS __attribute__((address_space(3)))
; DI f32x16 zero16() { f32x16 z; for (int i = 0; i < 16; ++i) z[i] = 0.f; return z; }
; #define MFMA32(a, b, c) __builtin_amdgcn_mfma_f32_32x32x16_bf16((a), (b), (c), 0, 0, 0)
; DI void sb_block2(const Params& p, LAS unsigned char* lds, int bh, int qb2, int tid) {
;     ...
;                 const int kb = kt * 64 + sub * 32;
;                 const LAS unsigned char* kp = base + (sub * 32 + r) * SB_ROW + h * 16;
;                 const bool act0 = !done[0] && kb <= q0[0], act1 = !done[1] && kb <= q0[1];
;                 if (act0 || act1) {
;                     bf16x8 kf[4], vf[4];
; #pragma unroll
;                     for (int ks = 0; ks < 4; ++ks) kf[ks] = *(const LAS bf16x8*)(kp + ks * 32);
; #pragma unroll
;                     for (int dt = 0; dt < 2; ++dt)
; #pragma unroll
;                         for (int s2 = 0; s2 < 2; ++s2) vf[dt * 2 + s2] = *(const LAS bf16x8*)(base + SB_KBYTES + (dt * 32 + r) * SB_ROW + (sub * 32 + 16 * h + 8 * s2) * 2);
;                     f32x16 zz[2];
; #pragma unroll
;                     for (int g = 0; g < 2; ++g) {
;                         zz[g] = zero16();
;                         if (g == 0 ? act0 : act1) {
; #pragma unroll
;                             for (int ks = 0; ks < 4; ++ks) zz[g] = MFMA32(kf[ks], qf[g][ks], zz[g]);
;                         }
;                     }
.LBB0_912:
	s_add_i32 s83, s3, 0
	s_add_i32 s82, s73, s79
	s_cmp_lt_i32 s82, s56
	s_cselect_b64 s[0:1], -1, 0
	s_xor_b64 s[2:3], s[62:63], -1
	s_and_b64 s[48:49], s[2:3], s[0:1]
	s_bitcmp1_b32 s81, 0
	s_cselect_b64 s[0:1], -1, 0
	s_cmp_lt_i32 s82, s58
	s_cselect_b64 s[2:3], -1, 0
	s_xor_b64 s[0:1], s[0:1], -1
	s_and_b64 s[2:3], s[0:1], s[2:3]
	v_add_u32_e32 v0, s83, v182
	s_or_b64 s[0:1], s[48:49], s[2:3]
	s_andn2_b64 vcc, exec, s[0:1]
	v_add_u32_e32 v196, v0, v188
	v_add3_u32 v195, s83, v188, v189
	s_cbranch_vccnz .LBB0_922
	ds_read_b128 v[174:177], v196 offset:4608
	ds_read_b128 v[170:173], v196 offset:4640
	ds_read_b128 v[166:169], v196 offset:4672
	ds_read_b128 v[162:165], v196 offset:4704
	ds_read_b128 v[158:161], v195 offset:9280
	ds_read_b128 v[150:153], v195 offset:9296
	ds_read_b128 v[154:157], v195 offset:13888
	ds_read_b128 v[146:149], v195 offset:13904
	v_cndmask_b32_e64 v0, 0, 1, s[48:49]
	v_cmp_ne_u32_e64 s[0:1], 1, v0
	s_andn2_b64 vcc, exec, s[48:49]
	s_cbranch_vccnz .LBB0_917
	s_waitcnt lgkmcnt(0)
	v_mfma_f32_32x32x16_bf16 v[18:33], v[174:177], v[114:117], 0
	v_mfma_f32_32x32x16_bf16 v[18:33], v[170:173], v[118:121], v[18:33]
	v_mfma_f32_32x32x16_bf16 v[18:33], v[166:169], v[122:125], v[18:33]
	v_mfma_f32_32x32x16_bf16 v[18:33], v[162:165], v[126:129], v[18:33]
	s_branch .LBB0_918

; #define LAS __attribute__((address_space(3)))
; DI f32x16 zero16() { f32x16 z; for (int i = 0; i < 16; ++i) z[i] = 0.f; return z; }
; #define MFMA32(a, b, c) __builtin_amdgcn_mfma_f32_32x32x16_bf16((a), (b), (c), 0, 0, 0)
; DI void sb_block2(const Params& p, LAS unsigned char* lds, int bh, int qb2, int tid) {
;     ...
;                 const int kb = kt * 64 + sub * 32;
;                 const LAS unsigned char* kp = base + (sub * 32 + r) * SB_ROW + h * 16;
;                 const bool act0 = !done[0] && kb <= q0[0], act1 = !done[1] && kb <= q0[1];
;                 if (act0 || act1) {
;                     bf16x8 kf[4], vf[4];
; #pragma unroll
;                     for (int ks = 0; ks < 4; ++ks) kf[ks] = *(const LAS bf16x8*)(kp + ks * 32);
; #pragma unroll
;                     for (int dt = 0; dt < 2; ++dt)
; #pragma unroll
;                         for (int s2 = 0; s2 < 2; ++s2) vf[dt * 2 + s2] = *(const LAS bf16x8*)(base + SB_KBYTES + (dt * 32 + r) * SB_ROW + (sub * 32 + 16 * h + 8 * s2) * 2);
;                     f32x16 zz[2];
; #pragma unroll
;                     for (int g = 0; g < 2; ++g) {
;                         zz[g] = zero16();
;                         if (g == 0 ? act0 : act1) {
; #pragma unroll
;                             for (int ks = 0; ks < 4; ++ks) zz[g] = MFMA32(kf[ks], qf[g][ks], zz[g]);
;                         }
;                     }
.LBB0_922:
	s_cmp_le_i32 s82, s56
	s_cselect_b64 s[0:1], -1, 0
	s_xor_b64 s[2:3], s[62:63], -1
	s_and_b64 s[48:49], s[2:3], s[0:1]
	s_bitcmp1_b32 s81, 0
	s_cselect_b64 s[0:1], -1, 0
	s_cmp_le_i32 s82, s58
	s_cselect_b64 s[2:3], -1, 0
	s_xor_b64 s[0:1], s[0:1], -1
	s_and_b64 s[2:3], s[0:1], s[2:3]
	s_or_b64 s[0:1], s[48:49], s[2:3]
	s_andn2_b64 vcc, exec, s[0:1]
	s_cbranch_vccnz .LBB0_850
	s_waitcnt lgkmcnt(0)
	ds_read_b128 v[174:177], v196
	ds_read_b128 v[170:173], v196 offset:32
	ds_read_b128 v[166:169], v196 offset:64
	ds_read_b128 v[162:165], v196 offset:96
	ds_read_b128 v[158:161], v195 offset:9216
	ds_read_b128 v[150:153], v195 offset:9232
	ds_read_b128 v[154:157], v195 offset:13824
	ds_read_b128 v[146:149], v195 offset:13840
	v_cndmask_b32_e64 v0, 0, 1, s[48:49]
	v_cmp_ne_u32_e64 s[0:1], 1, v0
	s_andn2_b64 vcc, exec, s[48:49]
	s_cbranch_vccnz .LBB0_927
	s_waitcnt lgkmcnt(0)
	v_mfma_f32_32x32x16_bf16 v[18:33], v[174:177], v[114:117], 0
	v_mfma_f32_32x32x16_bf16 v[18:33], v[170:173], v[118:121], v[18:33]
	v_mfma_f32_32x32x16_bf16 v[18:33], v[166:169], v[122:125], v[18:33]
	v_mfma_f32_32x32x16_bf16 v[18:33], v[162:165], v[126:129], v[18:33]
	s_branch .LBB0_928
